# leader-less XCD-local barrier (single per-XCC arrival counter, every CU polls it) at the 4 local seams instead of leader+generation word; mismatch flag read once after first barrier
# baseline (speedup 1.0000x reference)
; __device__ __forceinline__ void xcd_barrier(const XcdBarrier& b) {
;     ...
;         }
;     }
;     __syncthreads();
.LBB0_338:
	s_or_b64 exec, exec, s[2:3]
	s_waitcnt lgkmcnt(0)
	s_barrier
	v_mov_b32_e32 v253, 0x73800
	global_load_dword v253, v253, s[90:91] sc1

; #define PG8_STAGE(bufoff, gbase, voff) do { _Pragma("unroll") for (int _i = 0; _i < 2; ++_i) \
;         __builtin_amdgcn_global_load_lds((const unsigned*)((const char*)(gbase) + (voff)[_i]), (PG8_LAS unsigned*)(lds + (bufoff) + ldsw + _i * 8192), 16, 0, 0); } while (0)
; #define PG8_WAIT_V(n) asm volatile("s_waitcnt vmcnt(" #n ")" ::: "memory")
; #define PG8_BAR __builtin_amdgcn_s_barrier()
; template <class Epi, class Sched, bool ALIGN_EPI = false, bool SP2 = false>
; __device__ __forceinline__ void gemm_phase(PG8_LAS unsigned char* lds, const Gemm g, const Sched& S, const Epi& E) {
;     ...
;         PG8_STAGE(PG8_SB(1, 0), cB + kstep, voffB); PG8_STAGE(PG8_SA(1, 0), cA + kstep, voffA); PG8_STAGE(PG8_SB(1, 1), cB + hstep + kstep, voffB);
;         PG8_WAIT_V(6); PG8_BAR;
;     ...
;     for (;;) {
;         const bool has_next = S.next(ui + 1, nxt);
;         const char* nA = has_next ? (const char*)g.A + (size_t)nxt.pm * tstep : cA; const char* nB = has_next ? (const char*)g.Bt + (size_t)nxt.pn * tstep : cB;
;         for (int t = 0; t < nt; t += 2) {
.LBB0_345:
	s_mov_b64 s[20:21], 0x80
	s_add_i32 m0, s59, 0x18000
	v_lshl_add_u64 v[8:9], v[8:9], 0, s[20:21]
	s_waitcnt vmcnt(2)
	s_barrier
	global_load_lds_dwordx4 v[8:9], off
	v_lshl_add_u64 v[4:5], v[4:5], 0, s[20:21]
	s_add_i32 m0, s59, 0x1a000
	s_add_i32 s63, s59, 0x8000
	global_load_lds_dwordx4 v[4:5], off
	v_lshl_add_u64 v[4:5], v[6:7], 0, s[20:21]
	s_mov_b32 m0, s63
	s_add_i32 s64, s59, 0xa000
	global_load_lds_dwordx4 v[4:5], off
	v_lshl_add_u64 v[4:5], v[10:11], 0, s[20:21]
	s_mov_b32 m0, s64
	v_lshl_add_u64 v[2:3], v[2:3], 0, s[20:21]
	global_load_lds_dwordx4 v[4:5], off
	s_add_i32 m0, s59, 0x1c000
	v_lshl_add_u64 v[0:1], v[0:1], 0, s[20:21]
	global_load_lds_dwordx4 v[2:3], off
	s_add_i32 m0, s59, 0x1e000
	s_lshr_b32 s1, s1, 26
	global_load_lds_dwordx4 v[0:1], off
	s_and_b32 s2, s2, 3
	s_add_i32 s1, s0, s1
	s_ashr_i32 s65, s1, 6
	s_lshl_b32 s66, s3, 6
	s_lshl_b32 s1, s3, 13
	s_lshl_b32 s67, s2, 5
	s_cmp_gt_i32 s0, 63
	s_cselect_b64 s[22:23], -1, 0
	s_add_i32 s68, s65, -2
	s_cmpk_lt_u32 s11, 0x100
	s_cselect_b64 s[24:25], -1, 0
	s_add_u32 s69, s90, 0x9000000
	s_addc_u32 s70, s91, 0
	s_add_u32 s26, s90, 0x2600000
	s_addc_u32 s27, s91, 0
	s_add_u32 s28, s90, 0x3e00000
	s_addc_u32 s29, s91, 0
	s_add_u32 s30, s90, 0x2200000
	s_addc_u32 s31, s91, 0
	v_lshlrev_b32_e32 v1, 2, v201
	s_add_u32 s71, s88, 0x4000000
	v_lshl_or_b32 v0, v201, 6, v238
	v_and_b32_e32 v1, 32, v1
	s_addc_u32 s72, s89, 0
	v_bitop3_b32 v0, v0, s1, v1 bitop3:0xde
	s_add_u32 s34, s90, 0x20000
	v_add_u32_e32 v1, v237, v235
	s_addc_u32 s35, s91, 0
	v_mul_lo_u32 v1, s0, v1
	s_add_u32 s36, s90, 0x100000
	v_lshlrev_b32_e32 v1, 1, v1
	s_addc_u32 s37, s91, 0
	v_add3_u32 v136, v233, v1, v234
	v_add_u32_e32 v1, v236, v235
	s_cmp_gt_u32 s2, 1
	v_mul_lo_u32 v1, s0, v1
	s_waitcnt vmcnt(6)
	s_cselect_b64 s[38:39], -1, 0
	s_cmp_eq_u32 s2, 2
	v_lshlrev_b32_e32 v1, 1, v1
	v_lshl_or_b32 v170, s2, 12, v239
	s_cselect_b64 s[40:41], -1, 0
	v_lshl_add_u64 v[138:139], s[12:13], 0, v[136:137]
	v_add3_u32 v136, v233, v1, v234
	s_add_i32 s75, 0, 0x10000
	s_add_i32 s76, 0, 0x14000
	v_add_u32_e32 v173, 0, v0
	v_mbcnt_lo_u32_b32 v0, -1, 0
	s_ashr_i32 s73, s83, 31
	s_mov_b32 s86, s80
	s_ashr_i32 s74, s80, 31
	v_lshl_add_u64 v[140:141], s[12:13], 0, v[136:137]
	v_mov_b64_e32 v[142:143], 0xb80
	v_mov_b64_e32 v[144:145], 0xb7f
	v_add_u32_e32 v171, s75, v170
	v_add_u32_e32 v172, s76, v170
	s_movk_i32 s77, 0x300
	s_mov_b64 s[42:43], 0xcffe200
	s_mov_b32 s78, 0xcffe000
	v_mbcnt_hi_u32_b32 v174, -1, v0
	s_mov_b32 s79, 0
	s_barrier
	v_readfirstlane_b32 s98, v253
	s_mov_b32 s99, 0
	s_branch .LBB0_348

; __device__ __forceinline__ unsigned xb_ld(unsigned* p)              { return __hip_atomic_load(p, __ATOMIC_RELAXED, __HIP_MEMORY_SCOPE_AGENT); }
; __device__ __forceinline__ unsigned xb_add(unsigned* p, unsigned v) { return __hip_atomic_fetch_add(p, v, __ATOMIC_RELAXED, __HIP_MEMORY_SCOPE_AGENT); }
; #define XB_SPIN(cond, bar) do { unsigned _sp = 0; while (cond) { __builtin_amdgcn_s_sleep(1); \
;     if ((++_sp & 255u) == 0u) { if (xb_ld(&(bar)[XB_TMO])) break; if (_sp > XB_SPIN_CAP) { atomicAdd(&(bar)[XB_TMO], 1u); break; } } } } while (0)
; __device__ __forceinline__ void xcd_barrier(const XcdBarrier& b) {
;     asm volatile("s_waitcnt vmcnt(0)" ::: "memory");
;     __syncthreads();
;     if (threadIdx.x == 0) {
;         unsigned* bar = b.bar;
;         __builtin_amdgcn_s_waitcnt(0);
;         unsigned nloc = b.st[0], nx = b.st[1];
;         if (nloc == 0u) { xcd_barrier_complete(bar, b.x, nloc, nx); b.st[0] = nloc; b.st[1] = nx; }
;         const unsigned old = xb_add(&bar[XB_XSUB(b.x)], 1u);
;         const unsigned gen = old / nloc;
;         if (old + 1u == (gen + 1u) * nloc) {
;             __builtin_amdgcn_fence(__ATOMIC_RELEASE, "agent");
;             asm volatile("s_waitcnt vmcnt(0)" ::: "memory");
;             const unsigned og = xb_add(&bar[XB_TOP], 1u);
;             const unsigned tg = og / nx;
;             if (og + 1u == (tg + 1u) * nx) xb_add(&bar[XB_TOPGEN], 1u);
;             else XB_SPIN(xb_ld(&bar[XB_TOPGEN]) == tg, bar);
.LBB0_635:
	s_waitcnt vmcnt(0)
	s_waitcnt vmcnt(0) lgkmcnt(0)
	s_barrier
	s_mov_b64 s[0:1], exec
	v_readlane_b32 s2, v254, 5
	v_readlane_b32 s3, v254, 6
	s_and_b64 s[2:3], s[0:1], s[2:3]
	s_mov_b64 exec, s[2:3]
	s_cbranch_execz .LBB0_687
	s_cmp_lg_u32 s98, 0
	s_cbranch_scc1 .Lfb_orig_2
	v_readlane_b32 s4, v254, 4
	v_readlane_b32 s6, v254, 2
	v_readlane_b32 s7, v254, 3
	s_lshl_b32 s4, s4, 8
	s_add_u32 s4, s6, s4
	s_addc_u32 s5, s7, 0
	v_mov_b32_e32 v0, 0
	v_mov_b32_e32 v1, 1
	v_mov_b32_e32 v2, 0
	global_atomic_add v1, v0, v1, s[4:5] offset:1088 sc0
	s_waitcnt vmcnt(0)
	v_cmp_le_u32_e32 vcc, 31, v1
	s_cbranch_vccnz .Lfb_done_2
.Lfb_spin_2:
	global_load_dword v1, v0, s[4:5] offset:1088 sc1
	v_add_u32_e32 v2, 1, v2
	s_waitcnt vmcnt(0)
	v_cmp_le_u32_e32 vcc, 32, v1
	s_cbranch_vccnz .Lfb_done_2
	v_cmp_gt_u32_e32 vcc, 0x8000, v2
	s_cbranch_vccnz .Lfb_spin_2
.Lfb_done_2:
	buffer_inv sc1
	s_waitcnt vmcnt(0)
	s_branch .LBB0_687
.Lfb_orig_2:
	s_add_i32 s2, 0, 0x24040
	v_mov_b32_e32 v0, s2
	s_waitcnt vmcnt(0) expcnt(0) lgkmcnt(0)
	ds_read_b32 v2, v0
	s_add_i32 s2, 0, 0x24044
	v_mov_b32_e32 v0, s2
	ds_read_b32 v0, v0
	s_waitcnt lgkmcnt(1)
	v_cmp_ne_u32_e32 vcc, 0, v2
	s_cbranch_vccnz .LBB0_651
	v_readlane_b32 s2, v254, 0
	v_readlane_b32 s3, v254, 1
	s_load_dwordx2 s[6:7], s[2:3], 0x4
	s_add_u32 s2, s90, 0x70200
	s_addc_u32 s3, s91, 0
	s_add_u32 s4, s90, 0x70400
	s_addc_u32 s5, s91, 0
	s_waitcnt lgkmcnt(0)
	s_mul_i32 s33, s6, s83
	s_add_u32 s6, s90, 0x70500
	s_mul_i32 s33, s33, s7
	s_addc_u32 s7, s91, 0
	s_add_u32 s10, s90, 0x70600
	s_addc_u32 s11, s91, 0
	s_add_u32 s12, s90, 0x70700
	s_addc_u32 s13, s91, 0
	s_add_u32 s14, s90, 0x70800
	s_addc_u32 s15, s91, 0
	s_add_u32 s16, s90, 0x70900
	s_addc_u32 s17, s91, 0
	s_add_u32 s18, s90, 0x70a00
	s_addc_u32 s19, s91, 0
	s_add_u32 s20, s90, 0x70b00
	s_addc_u32 s21, s91, 0
	s_add_u32 s22, s90, 0x70c00
	s_addc_u32 s23, s91, 0
	s_add_u32 s24, s90, 0x70d00
	s_addc_u32 s25, s91, 0
	s_add_u32 s26, s90, 0x70e00
	s_addc_u32 s27, s91, 0
	s_add_u32 s28, s90, 0x70f00
	s_addc_u32 s29, s91, 0
	s_add_u32 s30, s90, 0x71000
	s_addc_u32 s31, s91, 0
	s_add_u32 s34, s90, 0x71100
	s_addc_u32 s35, s91, 0
	s_add_u32 s36, s90, 0x71200
	s_addc_u32 s37, s91, 0
	s_add_u32 s38, s90, 0x71300
	s_addc_u32 s39, s91, 0
	s_mov_b32 s46, 1
	v_mov_b32_e32 v16, 0
	s_branch .LBB0_639

; __device__ __forceinline__ unsigned xb_ld(unsigned* p)              { return __hip_atomic_load(p, __ATOMIC_RELAXED, __HIP_MEMORY_SCOPE_AGENT); }
; __device__ __forceinline__ unsigned xb_add(unsigned* p, unsigned v) { return __hip_atomic_fetch_add(p, v, __ATOMIC_RELAXED, __HIP_MEMORY_SCOPE_AGENT); }
; #define XB_SPIN(cond, bar) do { unsigned _sp = 0; while (cond) { __builtin_amdgcn_s_sleep(1); \
;     if ((++_sp & 255u) == 0u) { if (xb_ld(&(bar)[XB_TMO])) break; if (_sp > XB_SPIN_CAP) { atomicAdd(&(bar)[XB_TMO], 1u); break; } } } } while (0)
; __device__ __forceinline__ void xcd_barrier(const XcdBarrier& b) {
;     asm volatile("s_waitcnt vmcnt(0)" ::: "memory");
;     __syncthreads();
;     if (threadIdx.x == 0) {
;         unsigned* bar = b.bar;
;         __builtin_amdgcn_s_waitcnt(0);
;         unsigned nloc = b.st[0], nx = b.st[1];
;         if (nloc == 0u) { xcd_barrier_complete(bar, b.x, nloc, nx); b.st[0] = nloc; b.st[1] = nx; }
;         const unsigned old = xb_add(&bar[XB_XSUB(b.x)], 1u);
;         const unsigned gen = old / nloc;
;         if (old + 1u == (gen + 1u) * nloc) {
;             __builtin_amdgcn_fence(__ATOMIC_RELEASE, "agent");
;             asm volatile("s_waitcnt vmcnt(0)" ::: "memory");
;             const unsigned og = xb_add(&bar[XB_TOP], 1u);
;             const unsigned tg = og / nx;
;             if (og + 1u == (tg + 1u) * nx) xb_add(&bar[XB_TOPGEN], 1u);
;             else XB_SPIN(xb_ld(&bar[XB_TOPGEN]) == tg, bar);
.LBB0_1057:
	s_cmp_lt_i32 s92, 4
	s_cselect_b64 s[2:3], -1, 0
	s_cmp_gt_i32 s93, 4
	s_cselect_b64 s[0:1], -1, 0
	s_and_b64 s[2:3], s[2:3], s[0:1]
	s_andn2_b64 vcc, exec, s[2:3]
	s_cbranch_vccnz .LBB0_1111
	s_waitcnt vmcnt(0)
	s_waitcnt lgkmcnt(0)
	s_barrier
	s_mov_b64 s[2:3], exec
	v_readlane_b32 s4, v254, 5
	v_readlane_b32 s5, v254, 6
	s_and_b64 s[4:5], s[2:3], s[4:5]
	s_mov_b64 exec, s[4:5]
	s_cbranch_execz .LBB0_1110
	s_cmp_lg_u32 s98, 0
	s_cbranch_scc1 .Lfb_orig_4
	v_readlane_b32 s4, v254, 4
	v_readlane_b32 s6, v254, 2
	v_readlane_b32 s7, v254, 3
	s_lshl_b32 s4, s4, 8
	s_add_u32 s4, s6, s4
	s_addc_u32 s5, s7, 0
	v_mov_b32_e32 v0, 0
	v_mov_b32_e32 v1, 1
	v_mov_b32_e32 v2, 0
	global_atomic_add v1, v0, v1, s[4:5] offset:1088 sc0
	s_waitcnt vmcnt(0)
	v_cmp_le_u32_e32 vcc, 63, v1
	s_cbranch_vccnz .Lfb_done_4
.Lfb_spin_4:
	global_load_dword v1, v0, s[4:5] offset:1088 sc1
	v_add_u32_e32 v2, 1, v2
	s_waitcnt vmcnt(0)
	v_cmp_le_u32_e32 vcc, 64, v1
	s_cbranch_vccnz .Lfb_done_4
	v_cmp_gt_u32_e32 vcc, 0x8000, v2
	s_cbranch_vccnz .Lfb_spin_4

; __device__ __forceinline__ void xcd_barrier(const XcdBarrier& b) {
;     ...
;     if (threadIdx.x == 0) {
;         unsigned* bar = b.bar;
;         __builtin_amdgcn_s_waitcnt(0);
;         unsigned nloc = b.st[0], nx = b.st[1];
;         if (nloc == 0u) { xcd_barrier_complete(bar, b.x, nloc, nx); b.st[0] = nloc; b.st[1] = nx; }
.Lfb_orig_4:
	s_add_i32 s4, 0, 0x24040
	v_mov_b32_e32 v0, s4
	s_waitcnt vmcnt(0) expcnt(0) lgkmcnt(0)
	ds_read_b32 v2, v0
	s_add_i32 s4, 0, 0x24044
	v_mov_b32_e32 v0, s4
	ds_read_b32 v0, v0
	s_waitcnt lgkmcnt(1)
	v_cmp_ne_u32_e32 vcc, 0, v2
	s_cbranch_vccnz .LBB0_1074
	v_readlane_b32 s4, v254, 0
	v_readlane_b32 s5, v254, 1
	s_load_dwordx2 s[8:9], s[4:5], 0x4
	s_add_u32 s4, s90, 0x70200
	s_addc_u32 s5, s91, 0
	s_add_u32 s6, s90, 0x70400
	s_addc_u32 s7, s91, 0
	s_waitcnt lgkmcnt(0)
	s_mul_i32 s33, s8, s83
	s_add_u32 s8, s90, 0x70500
	s_mul_i32 s33, s33, s9
	s_addc_u32 s9, s91, 0
	s_add_u32 s10, s90, 0x70600
	s_addc_u32 s11, s91, 0
	s_add_u32 s12, s90, 0x70700
	s_addc_u32 s13, s91, 0
	s_add_u32 s14, s90, 0x70800
	s_addc_u32 s15, s91, 0
	s_add_u32 s16, s90, 0x70900
	s_addc_u32 s17, s91, 0
	s_add_u32 s18, s90, 0x70a00
	s_addc_u32 s19, s91, 0
	s_add_u32 s20, s90, 0x70b00
	s_addc_u32 s21, s91, 0
	s_add_u32 s22, s90, 0x70c00
	s_addc_u32 s23, s91, 0
	s_add_u32 s24, s90, 0x70d00
	s_addc_u32 s25, s91, 0
	s_add_u32 s26, s90, 0x70e00
	s_addc_u32 s27, s91, 0
	s_add_u32 s28, s90, 0x70f00
	s_addc_u32 s29, s91, 0
	s_add_u32 s30, s90, 0x71000
	s_addc_u32 s31, s91, 0
	s_add_u32 s34, s90, 0x71100
	s_addc_u32 s35, s91, 0
	s_add_u32 s36, s90, 0x71200
	s_addc_u32 s37, s91, 0
	s_add_u32 s38, s90, 0x71300
	s_addc_u32 s39, s91, 0
	s_mov_b32 s46, 1
	v_mov_b32_e32 v16, 0
	s_branch .LBB0_1062

; __device__ __forceinline__ unsigned xb_ld(unsigned* p)              { return __hip_atomic_load(p, __ATOMIC_RELAXED, __HIP_MEMORY_SCOPE_AGENT); }
; __device__ __forceinline__ unsigned xb_add(unsigned* p, unsigned v) { return __hip_atomic_fetch_add(p, v, __ATOMIC_RELAXED, __HIP_MEMORY_SCOPE_AGENT); }
; #define XB_SPIN(cond, bar) do { unsigned _sp = 0; while (cond) { __builtin_amdgcn_s_sleep(1); \
;     if ((++_sp & 255u) == 0u) { if (xb_ld(&(bar)[XB_TMO])) break; if (_sp > XB_SPIN_CAP) { atomicAdd(&(bar)[XB_TMO], 1u); break; } } } } while (0)
; __device__ __forceinline__ void xcd_barrier(const XcdBarrier& b) {
;     asm volatile("s_waitcnt vmcnt(0)" ::: "memory");
;     __syncthreads();
;     if (threadIdx.x == 0) {
;         unsigned* bar = b.bar;
;         __builtin_amdgcn_s_waitcnt(0);
;         unsigned nloc = b.st[0], nx = b.st[1];
;         if (nloc == 0u) { xcd_barrier_complete(bar, b.x, nloc, nx); b.st[0] = nloc; b.st[1] = nx; }
;         const unsigned old = xb_add(&bar[XB_XSUB(b.x)], 1u);
;         const unsigned gen = old / nloc;
;         if (old + 1u == (gen + 1u) * nloc) {
;             __builtin_amdgcn_fence(__ATOMIC_RELEASE, "agent");
;             asm volatile("s_waitcnt vmcnt(0)" ::: "memory");
;             const unsigned og = xb_add(&bar[XB_TOP], 1u);
;             const unsigned tg = og / nx;
;             if (og + 1u == (tg + 1u) * nx) xb_add(&bar[XB_TOPGEN], 1u);
;             else XB_SPIN(xb_ld(&bar[XB_TOPGEN]) == tg, bar);
.LBB0_1234:
	s_cmp_gt_i32 s93, 5
	s_cselect_b64 s[0:1], -1, 0
	s_and_b64 s[2:3], s[2:3], s[0:1]
	s_andn2_b64 vcc, exec, s[2:3]
	s_cbranch_vccnz .LBB0_1288
	s_waitcnt vmcnt(0)
	s_waitcnt lgkmcnt(0)
	s_barrier
	s_mov_b64 s[2:3], exec
	v_readlane_b32 s4, v254, 5
	v_readlane_b32 s5, v254, 6
	s_and_b64 s[4:5], s[2:3], s[4:5]
	s_mov_b64 exec, s[4:5]
	s_cbranch_execz .LBB0_1287
	s_cmp_lg_u32 s98, 0
	s_cbranch_scc1 .Lfb_orig_5
	v_readlane_b32 s4, v254, 4
	v_readlane_b32 s6, v254, 2
	v_readlane_b32 s7, v254, 3
	s_lshl_b32 s4, s4, 8
	s_add_u32 s4, s6, s4
	s_addc_u32 s5, s7, 0
	v_mov_b32_e32 v0, 0
	v_mov_b32_e32 v1, 1
	v_mov_b32_e32 v2, 0
	global_atomic_add v1, v0, v1, s[4:5] offset:1088 sc0
	s_waitcnt vmcnt(0)
	v_cmp_le_u32_e32 vcc, 95, v1
	s_cbranch_vccnz .Lfb_done_5
.Lfb_spin_5:
	global_load_dword v1, v0, s[4:5] offset:1088 sc1
	v_add_u32_e32 v2, 1, v2
	s_waitcnt vmcnt(0)
	v_cmp_le_u32_e32 vcc, 96, v1
	s_cbranch_vccnz .Lfb_done_5
	v_cmp_gt_u32_e32 vcc, 0x8000, v2
	s_cbranch_vccnz .Lfb_spin_5

; __device__ __forceinline__ unsigned xb_ld(unsigned* p)              { return __hip_atomic_load(p, __ATOMIC_RELAXED, __HIP_MEMORY_SCOPE_AGENT); }
; __device__ __forceinline__ unsigned xb_add(unsigned* p, unsigned v) { return __hip_atomic_fetch_add(p, v, __ATOMIC_RELAXED, __HIP_MEMORY_SCOPE_AGENT); }
; #define XB_SPIN(cond, bar) do { unsigned _sp = 0; while (cond) { __builtin_amdgcn_s_sleep(1); \
;     if ((++_sp & 255u) == 0u) { if (xb_ld(&(bar)[XB_TMO])) break; if (_sp > XB_SPIN_CAP) { atomicAdd(&(bar)[XB_TMO], 1u); break; } } } } while (0)
; __device__ __forceinline__ void xcd_barrier(const XcdBarrier& b) {
;     asm volatile("s_waitcnt vmcnt(0)" ::: "memory");
;     __syncthreads();
;     if (threadIdx.x == 0) {
;         unsigned* bar = b.bar;
;         __builtin_amdgcn_s_waitcnt(0);
;         unsigned nloc = b.st[0], nx = b.st[1];
;         if (nloc == 0u) { xcd_barrier_complete(bar, b.x, nloc, nx); b.st[0] = nloc; b.st[1] = nx; }
;         const unsigned old = xb_add(&bar[XB_XSUB(b.x)], 1u);
;         const unsigned gen = old / nloc;
;         if (old + 1u == (gen + 1u) * nloc) {
;             __builtin_amdgcn_fence(__ATOMIC_RELEASE, "agent");
;             asm volatile("s_waitcnt vmcnt(0)" ::: "memory");
;             const unsigned og = xb_add(&bar[XB_TOP], 1u);
;             const unsigned tg = og / nx;
;             if (og + 1u == (tg + 1u) * nx) xb_add(&bar[XB_TOPGEN], 1u);
;             else XB_SPIN(xb_ld(&bar[XB_TOPGEN]) == tg, bar);
.LBB0_1320:
	s_cmp_gt_i32 s93, 6
	s_cselect_b64 s[0:1], -1, 0
	s_and_b64 s[2:3], s[4:5], s[0:1]
	s_andn2_b64 vcc, exec, s[2:3]
	s_cbranch_vccnz .LBB0_1374
	s_waitcnt vmcnt(0)
	s_waitcnt lgkmcnt(0)
	s_barrier
	s_mov_b64 s[2:3], exec
	v_readlane_b32 s4, v254, 5
	v_readlane_b32 s5, v254, 6
	s_and_b64 s[4:5], s[2:3], s[4:5]
	s_mov_b64 exec, s[4:5]
	s_cbranch_execz .LBB0_1373
	s_cmp_lg_u32 s98, 0
	s_cbranch_scc1 .Lfb_orig_6
	v_readlane_b32 s4, v254, 4
	v_readlane_b32 s6, v254, 2
	v_readlane_b32 s7, v254, 3
	s_lshl_b32 s4, s4, 8
	s_add_u32 s4, s6, s4
	s_addc_u32 s5, s7, 0
	v_mov_b32_e32 v0, 0
	v_mov_b32_e32 v1, 1
	v_mov_b32_e32 v2, 0
	global_atomic_add v1, v0, v1, s[4:5] offset:1088 sc0
	s_waitcnt vmcnt(0)
	v_cmp_le_u32_e32 vcc, 127, v1
	s_cbranch_vccnz .Lfb_done_6
.Lfb_spin_6:
	global_load_dword v1, v0, s[4:5] offset:1088 sc1
	v_add_u32_e32 v2, 1, v2
	s_waitcnt vmcnt(0)
	v_cmp_le_u32_e32 vcc, 128, v1
	s_cbranch_vccnz .Lfb_done_6
	v_cmp_gt_u32_e32 vcc, 0x8000, v2
	s_cbranch_vccnz .Lfb_spin_6
